# plus: SGU main-step load hoisting extended to the first and last tile rows
# baseline (speedup 1.0000x reference)
.LBB0_767:
	s_or_b64 exec, exec, s[58:59]
	v_lshl_add_u64 v[98:99], v[92:93], 0, s[54:55]
	v_lshl_add_u64 v[100:101], v[90:91], 0, s[54:55]
	v_cvt_pk_bf16_f32 v2, v9, v8
	v_cvt_pk_bf16_f32 v3, v5, v4
	v_cvt_pk_bf16_f32 v4, v7, v6
	global_load_dwordx4 v[116:119], v[98:99], off offset:-128
	global_load_dwordx4 v[120:123], v[100:101], off offset:-128
	global_load_dwordx4 v[124:127], v[74:75], off offset:80
	global_load_dwordx4 v[128:131], v[74:75], off offset:64
	global_load_dwordx4 v[136:139], v[98:99], off offset:-96
	global_load_dwordx4 v[140:143], v[100:101], off offset:-96
	v_cvt_pk_bf16_f32 v5, v1, v0
	v_mov_b32_e32 v40, 0
	v_mov_b32_e32 v41, 0
	s_waitcnt vmcnt(5)
	v_mfma_f32_32x32x16_bf16 v[16:31], v[116:119], v[2:5], 0
	s_waitcnt vmcnt(4)
	v_mfma_f32_32x32x16_bf16 v[0:15], v[120:123], v[2:5], 0
	s_mov_b64 s[58:59], exec
	v_readlane_b32 s80, v254, 33
	v_readlane_b32 s81, v254, 34
	s_and_b64 s[80:81], s[58:59], s[80:81]
	s_mov_b64 exec, s[80:81]
	s_cbranch_execz .LBB0_769
	ds_read_b32 v41, v105 offset:64
	s_waitcnt vmcnt(2) lgkmcnt(0)
	v_mul_f32_e32 v41, v128, v41
.LBB0_769:
	s_or_b64 exec, exec, s[58:59]
	s_waitcnt vmcnt(2)
	v_mov_b32_e32 v36, 0
	s_mov_b64 s[58:59], exec
	v_readlane_b32 s80, v254, 35
	v_readlane_b32 s81, v254, 36
	s_and_b64 s[80:81], s[58:59], s[80:81]
	s_mov_b64 exec, s[80:81]
	s_cbranch_execz .LBB0_771
	ds_read_b32 v36, v105 offset:68
	s_waitcnt lgkmcnt(0)
	v_mul_f32_e32 v36, v129, v36
.LBB0_771:
	s_or_b64 exec, exec, s[58:59]
	s_mov_b64 s[58:59], exec
	v_readlane_b32 s80, v254, 37
	v_readlane_b32 s81, v254, 38
	s_and_b64 s[80:81], s[58:59], s[80:81]
	s_mov_b64 exec, s[80:81]
	s_cbranch_execz .LBB0_773
	ds_read_b32 v37, v105 offset:72
	s_waitcnt lgkmcnt(0)
	v_mul_f32_e32 v40, v130, v37
.LBB0_773:
	s_or_b64 exec, exec, s[58:59]
	v_mov_b32_e32 v37, 0
	v_mov_b32_e32 v38, 0
	s_mov_b64 s[58:59], exec
	v_readlane_b32 s80, v254, 39
	v_readlane_b32 s81, v254, 40
	s_and_b64 s[80:81], s[58:59], s[80:81]
	s_mov_b64 exec, s[80:81]
	s_cbranch_execz .LBB0_775
	ds_read_b32 v38, v105 offset:76
	s_waitcnt lgkmcnt(0)
	v_mul_f32_e32 v38, v131, v38
.LBB0_775:
	s_or_b64 exec, exec, s[58:59]
	s_mov_b64 s[58:59], exec
	v_readlane_b32 s80, v254, 41
	v_readlane_b32 s81, v254, 42
	s_and_b64 s[80:81], s[58:59], s[80:81]
	s_mov_b64 exec, s[80:81]
	s_cbranch_execz .LBB0_777
	ds_read_b32 v37, v105 offset:80
	s_waitcnt lgkmcnt(0)
	v_mul_f32_e32 v37, v124, v37
.LBB0_777:
	s_or_b64 exec, exec, s[58:59]
	v_mov_b32_e32 v32, 0
	v_mov_b32_e32 v39, 0
	s_mov_b64 s[58:59], exec
	v_readlane_b32 s80, v254, 43
	v_readlane_b32 s81, v254, 44
	s_and_b64 s[80:81], s[58:59], s[80:81]
	s_mov_b64 exec, s[80:81]
	s_cbranch_execz .LBB0_779
	ds_read_b32 v39, v105 offset:84
	s_waitcnt lgkmcnt(0)
	v_mul_f32_e32 v39, v125, v39
.LBB0_779:
	s_or_b64 exec, exec, s[58:59]
	s_mov_b64 s[58:59], exec
	v_readlane_b32 s80, v254, 45
	v_readlane_b32 s81, v254, 46
	s_and_b64 s[80:81], s[58:59], s[80:81]
	s_mov_b64 exec, s[80:81]
	s_cbranch_execz .LBB0_781
	ds_read_b32 v32, v105 offset:88
	s_waitcnt lgkmcnt(0)
	v_mul_f32_e32 v32, v126, v32
.LBB0_781:
	s_or_b64 exec, exec, s[58:59]
	v_mov_b32_e32 v56, 0
	v_mov_b32_e32 v33, 0
	s_mov_b64 s[58:59], exec
	v_readlane_b32 s80, v254, 47
	v_readlane_b32 s81, v254, 48
	s_and_b64 s[80:81], s[58:59], s[80:81]
	s_mov_b64 exec, s[80:81]
	s_cbranch_execz .LBB0_783
	ds_read_b32 v33, v105 offset:92
	s_waitcnt lgkmcnt(0)
	v_mul_f32_e32 v33, v127, v33
.LBB0_783:
	s_or_b64 exec, exec, s[58:59]
	v_cvt_pk_bf16_f32 v34, v41, v36
	v_cvt_pk_bf16_f32 v35, v40, v38
	v_cvt_pk_bf16_f32 v36, v37, v39
	v_cvt_pk_bf16_f32 v37, v32, v33
	v_lshl_add_u64 v[102:103], v[94:95], 0, s[54:55]
	s_brev_b32 s51, 48
	global_load_dword v32, v[76:77], off
	s_waitcnt vmcnt(2)
	v_mfma_f32_32x32x16_bf16 v[16:31], v[136:139], v[34:37], v[16:31]
	s_waitcnt vmcnt(0)
	s_nop 10
	v_pk_add_f32 v[16:17], v[16:17], v[32:33] op_sel_hi:[1,0]
	v_mfma_f32_32x32x16_bf16 v[0:15], v[140:143], v[34:37], v[0:15]
	v_add_co_u32_e32 v34, vcc, s51, v102
	v_add_f32_e64 v18, v18, v32
	v_add_f32_e64 v19, v19, v32
	v_addc_co_u32_e32 v35, vcc, 0, v103, vcc
	global_load_dwordx2 v[116:117], v[34:35], off
	global_load_dwordx2 v[118:119], v[34:35], off offset:16
	global_load_dwordx2 v[120:121], v[34:35], off offset:32
	global_load_dwordx2 v[122:123], v[34:35], off offset:48
	global_load_dwordx2 v[124:125], v[34:35], off offset:64
	global_load_dwordx2 v[126:127], v[34:35], off offset:80
	global_load_dwordx2 v[128:129], v[34:35], off offset:96
	global_load_dwordx2 v[130:131], v[34:35], off offset:112
	s_mov_b32 s51, 0x1a000000
	v_pk_add_f32 v[20:21], v[20:21], v[32:33] op_sel_hi:[1,0]
	v_pk_add_f32 v[22:23], v[22:23], v[32:33] op_sel_hi:[1,0]
	s_nop 3
	v_pk_add_f32 v[0:1], v[32:33], v[0:1] op_sel_hi:[0,1]
	v_pk_add_f32 v[2:3], v[32:33], v[2:3] op_sel_hi:[0,1]
	v_pk_add_f32 v[4:5], v[32:33], v[4:5] op_sel_hi:[0,1]
	s_waitcnt vmcnt(7)
	v_lshlrev_b32_e32 v38, 16, v116
	v_and_b32_e32 v39, 0xffff0000, v116
	v_pk_mul_f32 v[16:17], v[16:17], v[38:39]
	s_nop 0
	v_cvt_pk_bf16_f32 v36, v16, v17
	v_lshlrev_b32_e32 v16, 16, v117
	v_and_b32_e32 v17, 0xffff0000, v117
	v_pk_mul_f32 v[16:17], v[18:19], v[16:17]
	v_cvt_pk_bf16_f32 v37, v16, v17
	v_add_co_u32_e32 v16, vcc, s51, v102
	s_nop 1
	v_addc_co_u32_e32 v17, vcc, 0, v103, vcc
	global_store_dwordx2 v[16:17], v[36:37], off
	s_waitcnt vmcnt(7)
	v_lshlrev_b32_e32 v36, 16, v118
	v_and_b32_e32 v37, 0xffff0000, v118
	v_pk_mul_f32 v[20:21], v[20:21], v[36:37]
	s_nop 0
	v_cvt_pk_bf16_f32 v18, v20, v21
	v_lshlrev_b32_e32 v20, 16, v119
	v_and_b32_e32 v21, 0xffff0000, v119
	v_pk_mul_f32 v[20:21], v[22:23], v[20:21]
	v_pk_add_f32 v[22:23], v[24:25], v[32:33] op_sel_hi:[1,0]
	v_cvt_pk_bf16_f32 v19, v20, v21
	global_store_dwordx2 v[16:17], v[18:19], off offset:16
	s_waitcnt vmcnt(7)
	v_lshlrev_b32_e32 v20, 16, v120
	v_and_b32_e32 v21, 0xffff0000, v120
	v_pk_mul_f32 v[20:21], v[22:23], v[20:21]
	v_pk_add_f32 v[22:23], v[26:27], v[32:33] op_sel_hi:[1,0]
	v_cvt_pk_bf16_f32 v18, v20, v21
	v_lshlrev_b32_e32 v20, 16, v121
	v_and_b32_e32 v21, 0xffff0000, v121
	v_pk_mul_f32 v[20:21], v[22:23], v[20:21]
	v_pk_add_f32 v[22:23], v[28:29], v[32:33] op_sel_hi:[1,0]
	v_cvt_pk_bf16_f32 v19, v20, v21
	global_store_dwordx2 v[16:17], v[18:19], off offset:32
	s_waitcnt vmcnt(7)
	v_lshlrev_b32_e32 v20, 16, v122
	v_and_b32_e32 v21, 0xffff0000, v122
	v_pk_mul_f32 v[20:21], v[22:23], v[20:21]
	v_pk_add_f32 v[22:23], v[30:31], v[32:33] op_sel_hi:[1,0]
	v_cvt_pk_bf16_f32 v18, v20, v21
	v_lshlrev_b32_e32 v20, 16, v123
	v_and_b32_e32 v21, 0xffff0000, v123
	v_pk_mul_f32 v[20:21], v[22:23], v[20:21]
	s_nop 0
	v_cvt_pk_bf16_f32 v19, v20, v21
	global_store_dwordx2 v[16:17], v[18:19], off offset:48
	s_waitcnt vmcnt(7)
	v_lshlrev_b32_e32 v20, 16, v124
	v_and_b32_e32 v21, 0xffff0000, v124
	v_lshlrev_b32_e32 v18, 16, v125
	v_and_b32_e32 v19, 0xffff0000, v125
	v_pk_mul_f32 v[0:1], v[0:1], v[20:21]
	v_pk_mul_f32 v[2:3], v[2:3], v[18:19]
	v_cvt_pk_bf16_f32 v0, v0, v1
	v_cvt_pk_bf16_f32 v1, v2, v3
	global_store_dwordx2 v[16:17], v[0:1], off offset:64
	s_waitcnt vmcnt(7)
	v_lshlrev_b32_e32 v2, 16, v126
	v_and_b32_e32 v3, 0xffff0000, v126
	v_pk_mul_f32 v[2:3], v[4:5], v[2:3]
	v_pk_add_f32 v[4:5], v[32:33], v[6:7] op_sel_hi:[0,1]
	v_cvt_pk_bf16_f32 v0, v2, v3
	v_lshlrev_b32_e32 v2, 16, v127
	v_and_b32_e32 v3, 0xffff0000, v127
	v_pk_mul_f32 v[2:3], v[4:5], v[2:3]
	v_pk_add_f32 v[4:5], v[32:33], v[8:9] op_sel_hi:[0,1]
	v_cvt_pk_bf16_f32 v1, v2, v3
	global_store_dwordx2 v[16:17], v[0:1], off offset:80
	s_waitcnt vmcnt(7)
	v_lshlrev_b32_e32 v2, 16, v128
	v_and_b32_e32 v3, 0xffff0000, v128
	v_pk_mul_f32 v[2:3], v[4:5], v[2:3]
	v_pk_add_f32 v[4:5], v[32:33], v[10:11] op_sel_hi:[0,1]
	v_cvt_pk_bf16_f32 v0, v2, v3
	v_lshlrev_b32_e32 v2, 16, v129
	v_and_b32_e32 v3, 0xffff0000, v129
	v_pk_mul_f32 v[2:3], v[4:5], v[2:3]
	v_pk_add_f32 v[4:5], v[32:33], v[12:13] op_sel_hi:[0,1]
	v_cvt_pk_bf16_f32 v1, v2, v3
	global_store_dwordx2 v[16:17], v[0:1], off offset:96
	s_waitcnt vmcnt(7)
	v_lshlrev_b32_e32 v2, 16, v130
	v_and_b32_e32 v3, 0xffff0000, v130
	v_pk_mul_f32 v[2:3], v[4:5], v[2:3]
	v_pk_add_f32 v[4:5], v[32:33], v[14:15] op_sel_hi:[0,1]
	v_cvt_pk_bf16_f32 v0, v2, v3
	v_lshlrev_b32_e32 v2, 16, v131
	v_and_b32_e32 v3, 0xffff0000, v131
	v_pk_mul_f32 v[2:3], v[4:5], v[2:3]
	s_nop 0
	v_cvt_pk_bf16_f32 v1, v2, v3
	global_store_dwordx2 v[16:17], v[0:1], off offset:112
	global_load_dwordx4 v[116:119], v[78:79], off offset:16
	global_load_dwordx4 v[120:123], v[78:79], off
	global_load_dwordx4 v[124:127], v[98:99], off offset:-128
	global_load_dwordx4 v[128:131], v[100:101], off offset:-128
	global_load_dwordx4 v[136:139], v[78:79], off offset:80
	global_load_dwordx4 v[140:143], v[78:79], off offset:64
	global_load_dwordx4 v[144:147], v[98:99], off offset:-96
	global_load_dwordx4 v[148:151], v[100:101], off offset:-96
	global_load_dwordx4 v[152:155], v[78:79], off offset:144
	global_load_dwordx4 v[156:159], v[78:79], off offset:128
	global_load_dwordx4 v[160:163], v[98:99], off offset:-64
	global_load_dwordx4 v[164:167], v[100:101], off offset:-64
	global_load_dwordx4 v[184:187], v[78:79], off offset:208
	global_load_dwordx4 v[188:191], v[78:79], off offset:192
	global_load_dwordx4 v[192:195], v[98:99], off offset:-32
	global_load_dwordx4 v[196:199], v[100:101], off offset:-32
	s_nop 0
	ds_read_b128 v[36:39], v105
	ds_read_b128 v[32:35], v105 offset:16
	s_waitcnt vmcnt(15) lgkmcnt(0)
	v_pk_mul_f32 v[8:9], v[116:117], v[32:33]
	s_waitcnt vmcnt(14)
	v_pk_mul_f32 v[4:5], v[120:121], v[36:37]
	v_pk_mul_f32 v[6:7], v[122:123], v[38:39]
	v_pk_mul_f32 v[10:11], v[118:119], v[34:35]
	v_cvt_pk_bf16_f32 v0, v4, v5
	v_cvt_pk_bf16_f32 v1, v6, v7
	v_cvt_pk_bf16_f32 v2, v8, v9
	v_cvt_pk_bf16_f32 v3, v10, v11
	ds_read_b128 v[40:43], v105 offset:64
	s_waitcnt vmcnt(13)
	v_mfma_f32_32x32x16_bf16 v[16:31], v[124:127], v[0:3], 0
	s_waitcnt vmcnt(10) lgkmcnt(0)
	v_mul_f32_e64 v52, v140, v40
	v_mul_f32_e64 v53, v141, v41
	v_mul_f32_e64 v54, v142, v42
	v_mul_f32_e64 v55, v143, v43
	ds_read_b128 v[44:47], v105 offset:80
	s_waitcnt lgkmcnt(0)
	v_pk_mul_f32 v[58:59], v[136:137], v[44:45]
	v_pk_mul_f32 v[60:61], v[138:139], v[46:47]
	v_cvt_pk_bf16_f32 v48, v52, v53
	v_cvt_pk_bf16_f32 v49, v54, v55
	v_cvt_pk_bf16_f32 v50, v58, v59
	v_cvt_pk_bf16_f32 v51, v60, v61
	v_mfma_f32_32x32x16_bf16 v[0:15], v[128:131], v[0:3], 0
	s_waitcnt vmcnt(9)
	v_mfma_f32_32x32x16_bf16 v[16:31], v[144:147], v[48:51], v[16:31]
	s_waitcnt vmcnt(8)
	v_mfma_f32_32x32x16_bf16 v[0:15], v[148:151], v[48:51], v[0:15]
	s_mov_b64 s[58:59], exec
	v_readlane_b32 s80, v254, 49
	v_readlane_b32 s81, v254, 50
	s_and_b64 s[80:81], s[58:59], s[80:81]
	s_mov_b64 exec, s[80:81]
	s_cbranch_execz .LBB0_785
	ds_read_b32 v56, v105 offset:128
	s_waitcnt vmcnt(6) lgkmcnt(0)
	v_mul_f32_e32 v56, v156, v56

.LBB0_847:
	s_or_b64 exec, exec, s[58:59]
	v_cvt_pk_bf16_f32 v107, v68, v70
	v_cvt_pk_bf16_f32 v108, v69, v71
	v_cvt_pk_bf16_f32 v109, v64, v66
	v_cvt_pk_bf16_f32 v106, v106, v87
	s_mov_b32 s51, 0xc010000
	global_load_dword v64, v[76:77], off offset:256
	s_waitcnt vmcnt(2)
	v_mfma_f32_32x32x16_bf16 v[16:31], v[232:235], v[106:109], v[16:31]
	v_add_co_u32_e32 v66, vcc, s51, v102
	s_mov_b32 s51, 0x1a010000
	s_nop 0
	v_addc_co_u32_e32 v67, vcc, 0, v103, vcc
	global_load_dwordx2 v[116:117], v[66:67], off
	global_load_dwordx2 v[118:119], v[66:67], off offset:16
	global_load_dwordx2 v[120:121], v[66:67], off offset:32
	global_load_dwordx2 v[122:123], v[66:67], off offset:48
	global_load_dwordx2 v[124:125], v[66:67], off offset:64
	global_load_dwordx2 v[126:127], v[66:67], off offset:80
	global_load_dwordx2 v[128:129], v[66:67], off offset:96
	global_load_dwordx2 v[130:131], v[66:67], off offset:112
	s_waitcnt vmcnt(1)
	s_nop 5
	v_pk_add_f32 v[16:17], v[16:17], v[64:65] op_sel_hi:[1,0]
	v_pk_add_f32 v[18:19], v[18:19], v[64:65] op_sel_hi:[1,0]
	v_pk_add_f32 v[20:21], v[20:21], v[64:65] op_sel_hi:[1,0]
	v_pk_add_f32 v[22:23], v[22:23], v[64:65] op_sel_hi:[1,0]
	v_mfma_f32_32x32x16_bf16 v[0:15], v[236:239], v[106:109], v[0:15]
	s_waitcnt vmcnt(7)
	v_lshlrev_b32_e32 v70, 16, v116
	v_and_b32_e32 v71, 0xffff0000, v116
	v_mul_f32_e64 v16, v16, v70
	v_mul_f32_e64 v17, v17, v71
	s_nop 6
	v_pk_add_f32 v[0:1], v[64:65], v[0:1] op_sel_hi:[0,1]
	v_cvt_pk_bf16_f32 v68, v16, v17
	v_lshlrev_b32_e32 v16, 16, v117
	v_and_b32_e32 v17, 0xffff0000, v117
	v_pk_mul_f32 v[16:17], v[18:19], v[16:17]
	v_cvt_pk_bf16_f32 v69, v16, v17
	v_add_co_u32_e32 v16, vcc, s51, v102
	v_pk_add_f32 v[2:3], v[64:65], v[2:3] op_sel_hi:[0,1]
	s_nop 0
	v_addc_co_u32_e32 v17, vcc, 0, v103, vcc
	global_store_dwordx2 v[16:17], v[68:69], off
	v_pk_add_f32 v[4:5], v[64:65], v[4:5] op_sel_hi:[0,1]
	s_waitcnt vmcnt(7)
	v_lshlrev_b32_e32 v68, 16, v118
	v_and_b32_e32 v69, 0xffff0000, v118
	v_pk_mul_f32 v[20:21], v[20:21], v[68:69]
	s_nop 0
	v_cvt_pk_bf16_f32 v18, v20, v21
	v_lshlrev_b32_e32 v20, 16, v119
	v_and_b32_e32 v21, 0xffff0000, v119
	v_pk_mul_f32 v[20:21], v[22:23], v[20:21]
	v_pk_add_f32 v[22:23], v[24:25], v[64:65] op_sel_hi:[1,0]
	v_cvt_pk_bf16_f32 v19, v20, v21
	global_store_dwordx2 v[16:17], v[18:19], off offset:16
	s_waitcnt vmcnt(7)
	v_lshlrev_b32_e32 v20, 16, v120
	v_and_b32_e32 v21, 0xffff0000, v120
	v_pk_mul_f32 v[20:21], v[22:23], v[20:21]
	v_pk_add_f32 v[22:23], v[26:27], v[64:65] op_sel_hi:[1,0]
	v_cvt_pk_bf16_f32 v18, v20, v21
	v_lshlrev_b32_e32 v20, 16, v121
	v_and_b32_e32 v21, 0xffff0000, v121
	v_pk_mul_f32 v[20:21], v[22:23], v[20:21]
	v_pk_add_f32 v[22:23], v[28:29], v[64:65] op_sel_hi:[1,0]
	v_cvt_pk_bf16_f32 v19, v20, v21
	global_store_dwordx2 v[16:17], v[18:19], off offset:32
	s_waitcnt vmcnt(7)
	v_lshlrev_b32_e32 v20, 16, v122
	v_and_b32_e32 v21, 0xffff0000, v122
	v_pk_mul_f32 v[20:21], v[22:23], v[20:21]
	v_pk_add_f32 v[22:23], v[30:31], v[64:65] op_sel_hi:[1,0]
	v_cvt_pk_bf16_f32 v18, v20, v21
	v_lshlrev_b32_e32 v20, 16, v123
	v_and_b32_e32 v21, 0xffff0000, v123
	v_pk_mul_f32 v[20:21], v[22:23], v[20:21]
	s_nop 0
	v_cvt_pk_bf16_f32 v19, v20, v21
	global_store_dwordx2 v[16:17], v[18:19], off offset:48
	s_waitcnt vmcnt(7)
	v_lshlrev_b32_e32 v20, 16, v124
	v_and_b32_e32 v21, 0xffff0000, v124
	v_lshlrev_b32_e32 v18, 16, v125
	v_and_b32_e32 v19, 0xffff0000, v125
	v_pk_mul_f32 v[0:1], v[0:1], v[20:21]
	v_pk_mul_f32 v[2:3], v[2:3], v[18:19]
	v_cvt_pk_bf16_f32 v0, v0, v1
	v_cvt_pk_bf16_f32 v1, v2, v3
	global_store_dwordx2 v[16:17], v[0:1], off offset:64
	s_waitcnt vmcnt(7)
	v_lshlrev_b32_e32 v2, 16, v126
	v_and_b32_e32 v3, 0xffff0000, v126
	v_pk_mul_f32 v[2:3], v[4:5], v[2:3]
	v_pk_add_f32 v[4:5], v[64:65], v[6:7] op_sel_hi:[0,1]
	v_cvt_pk_bf16_f32 v0, v2, v3
	v_lshlrev_b32_e32 v2, 16, v127
	v_and_b32_e32 v3, 0xffff0000, v127
	v_pk_mul_f32 v[2:3], v[4:5], v[2:3]
	v_pk_add_f32 v[4:5], v[64:65], v[8:9] op_sel_hi:[0,1]
	v_cvt_pk_bf16_f32 v1, v2, v3
	global_store_dwordx2 v[16:17], v[0:1], off offset:80
	s_waitcnt vmcnt(7)
	v_lshlrev_b32_e32 v2, 16, v128
	v_and_b32_e32 v3, 0xffff0000, v128
	v_pk_mul_f32 v[2:3], v[4:5], v[2:3]
	v_pk_add_f32 v[4:5], v[64:65], v[10:11] op_sel_hi:[0,1]
	v_cvt_pk_bf16_f32 v0, v2, v3
	v_lshlrev_b32_e32 v2, 16, v129
	v_and_b32_e32 v3, 0xffff0000, v129
	v_pk_mul_f32 v[2:3], v[4:5], v[2:3]
	v_pk_add_f32 v[4:5], v[64:65], v[12:13] op_sel_hi:[0,1]
	v_cvt_pk_bf16_f32 v1, v2, v3
	global_store_dwordx2 v[16:17], v[0:1], off offset:96
	s_waitcnt vmcnt(7)
	v_lshlrev_b32_e32 v2, 16, v130
	v_and_b32_e32 v3, 0xffff0000, v130
	v_pk_mul_f32 v[2:3], v[4:5], v[2:3]
	v_pk_add_f32 v[4:5], v[64:65], v[14:15] op_sel_hi:[0,1]
	v_cvt_pk_bf16_f32 v0, v2, v3
	v_lshlrev_b32_e32 v2, 16, v131
	v_and_b32_e32 v3, 0xffff0000, v131
	v_pk_mul_f32 v[2:3], v[4:5], v[2:3]
	s_nop 0
	v_cvt_pk_bf16_f32 v1, v2, v3
	global_store_dwordx2 v[16:17], v[0:1], off offset:112
	global_load_dwordx4 v[116:119], v[84:85], off offset:16
	global_load_dwordx4 v[120:123], v[84:85], off
	global_load_dwordx4 v[124:127], v[98:99], off offset:-128
	global_load_dwordx4 v[128:131], v[100:101], off offset:-128
	global_load_dwordx4 v[136:139], v[84:85], off offset:80
	global_load_dwordx4 v[140:143], v[84:85], off offset:64
	global_load_dwordx4 v[144:147], v[98:99], off offset:-96
	global_load_dwordx4 v[148:151], v[100:101], off offset:-96
	global_load_dwordx4 v[152:155], v[84:85], off offset:144
	global_load_dwordx4 v[156:159], v[84:85], off offset:128
	global_load_dwordx4 v[160:163], v[98:99], off offset:-64
	global_load_dwordx4 v[164:167], v[100:101], off offset:-64
	global_load_dwordx4 v[184:187], v[84:85], off offset:208
	global_load_dwordx4 v[188:191], v[84:85], off offset:192
	global_load_dwordx4 v[192:195], v[98:99], off offset:-32
	global_load_dwordx4 v[196:199], v[100:101], off offset:-32
	global_load_dwordx4 v[200:203], v[84:85], off offset:272
	global_load_dwordx4 v[204:207], v[84:85], off offset:256
	global_load_dwordx4 v[208:211], v[98:99], off
	global_load_dwordx4 v[214:217], v[100:101], off
	s_nop 0
	s_waitcnt vmcnt(19)
	v_pk_mul_f32 v[8:9], v[32:33], v[116:117]
	s_waitcnt vmcnt(18)
	v_pk_mul_f32 v[4:5], v[36:37], v[120:121]
	v_pk_mul_f32 v[6:7], v[38:39], v[122:123]
	v_pk_mul_f32 v[10:11], v[34:35], v[118:119]
	v_cvt_pk_bf16_f32 v0, v4, v5
	v_cvt_pk_bf16_f32 v1, v6, v7
	v_cvt_pk_bf16_f32 v2, v8, v9
	v_cvt_pk_bf16_f32 v3, v10, v11
	s_waitcnt vmcnt(17)
	v_mfma_f32_32x32x16_bf16 v[16:31], v[124:127], v[0:3], 0
	s_waitcnt vmcnt(14)
	v_mul_f32_e64 v36, v40, v140
	v_mul_f32_e64 v37, v41, v141
	v_mul_f32_e64 v38, v42, v142
	v_mul_f32_e64 v39, v43, v143
	v_pk_mul_f32 v[40:41], v[44:45], v[136:137]
	v_pk_mul_f32 v[42:43], v[46:47], v[138:139]
	v_cvt_pk_bf16_f32 v32, v36, v37
	v_cvt_pk_bf16_f32 v33, v38, v39
	v_cvt_pk_bf16_f32 v34, v40, v41
	v_cvt_pk_bf16_f32 v35, v42, v43
	v_mfma_f32_32x32x16_bf16 v[0:15], v[128:131], v[0:3], 0
	s_waitcnt vmcnt(13)
	v_mfma_f32_32x32x16_bf16 v[16:31], v[144:147], v[32:35], v[16:31]
	s_waitcnt vmcnt(12)
	v_mfma_f32_32x32x16_bf16 v[0:15], v[148:151], v[32:35], v[0:15]
	s_waitcnt vmcnt(11)
	v_mul_f32_e64 v40, v48, v152
	v_mul_f32_e64 v41, v49, v153
	s_waitcnt vmcnt(10)
	v_pk_mul_f32 v[36:37], v[52:53], v[156:157]
	v_pk_mul_f32 v[38:39], v[54:55], v[158:159]
	v_pk_mul_f32 v[42:43], v[50:51], v[154:155]
	v_cvt_pk_bf16_f32 v32, v36, v37
	v_cvt_pk_bf16_f32 v33, v38, v39
	v_cvt_pk_bf16_f32 v34, v40, v41
	v_cvt_pk_bf16_f32 v35, v42, v43
	s_waitcnt vmcnt(9)
	v_mfma_f32_32x32x16_bf16 v[16:31], v[160:163], v[32:35], v[16:31]
	s_waitcnt vmcnt(8)
	v_mfma_f32_32x32x16_bf16 v[0:15], v[164:167], v[32:35], v[0:15]
	s_waitcnt vmcnt(7)
	v_mul_f32_e64 v40, v60, v184
	v_mul_f32_e64 v41, v61, v185
	s_waitcnt vmcnt(6)
	v_pk_mul_f32 v[36:37], v[56:57], v[188:189]
	v_pk_mul_f32 v[38:39], v[58:59], v[190:191]
	v_pk_mul_f32 v[42:43], v[62:63], v[186:187]
	v_cvt_pk_bf16_f32 v32, v36, v37
	v_cvt_pk_bf16_f32 v33, v38, v39
	v_cvt_pk_bf16_f32 v34, v40, v41
	v_cvt_pk_bf16_f32 v35, v42, v43
	s_waitcnt vmcnt(5)
	v_mfma_f32_32x32x16_bf16 v[16:31], v[192:195], v[32:35], v[16:31]
	s_waitcnt vmcnt(4)
	v_mfma_f32_32x32x16_bf16 v[0:15], v[196:199], v[32:35], v[0:15]
	ds_read_b128 v[40:43], v105 offset:256
	ds_read_b128 v[44:47], v105 offset:272
	s_waitcnt vmcnt(2) lgkmcnt(1)
	v_pk_mul_f32 v[36:37], v[204:205], v[40:41]
	v_pk_mul_f32 v[38:39], v[206:207], v[42:43]
	s_waitcnt lgkmcnt(0)
	v_pk_mul_f32 v[40:41], v[200:201], v[44:45]
	v_pk_mul_f32 v[42:43], v[202:203], v[46:47]
	v_cvt_pk_bf16_f32 v32, v36, v37
	v_cvt_pk_bf16_f32 v33, v38, v39
	v_cvt_pk_bf16_f32 v34, v40, v41
	v_cvt_pk_bf16_f32 v35, v42, v43
	s_waitcnt vmcnt(1)
	v_mfma_f32_32x32x16_bf16 v[16:31], v[208:211], v[32:35], v[16:31]
	s_waitcnt vmcnt(0)
	v_mfma_f32_32x32x16_bf16 v[0:15], v[214:217], v[32:35], v[0:15]
	global_load_dwordx4 v[116:119], v[84:85], off offset:336
	global_load_dwordx4 v[120:123], v[84:85], off offset:320
	global_load_dwordx4 v[124:127], v[98:99], off offset:32
	global_load_dwordx4 v[128:131], v[100:101], off offset:32
	global_load_dwordx4 v[136:139], v[84:85], off offset:400
	global_load_dwordx4 v[140:143], v[84:85], off offset:384
	global_load_dwordx4 v[144:147], v[98:99], off offset:64
	global_load_dwordx4 v[148:151], v[100:101], off offset:64
	ds_read_b128 v[40:43], v105 offset:320
	s_waitcnt vmcnt(6) lgkmcnt(0)
	v_mul_f32_e64 v40, v120, v40
	v_mul_f32_e64 v41, v121, v41
	v_pk_mul_f32 v[42:43], v[122:123], v[42:43]
	ds_read_b128 v[36:39], v105 offset:336
	s_waitcnt lgkmcnt(0)
	v_pk_mul_f32 v[36:37], v[116:117], v[36:37]
	v_pk_mul_f32 v[38:39], v[118:119], v[38:39]
	v_cvt_pk_bf16_f32 v32, v40, v41
	v_cvt_pk_bf16_f32 v33, v42, v43
	v_cvt_pk_bf16_f32 v34, v36, v37
	v_cvt_pk_bf16_f32 v35, v38, v39
	s_waitcnt vmcnt(5)
	v_mfma_f32_32x32x16_bf16 v[16:31], v[124:127], v[32:35], v[16:31]
	s_waitcnt vmcnt(4)
	v_mfma_f32_32x32x16_bf16 v[0:15], v[128:131], v[32:35], v[0:15]
	s_and_saveexec_b64 s[58:59], s[0:1]
	s_cbranch_execz .LBB0_849
	ds_read_b32 v40, v105 offset:384
	s_waitcnt vmcnt(2) lgkmcnt(0)
	v_mul_f32_e32 v65, v140, v40
.LBB0_849:
	s_or_b64 exec, exec, s[58:59]
	s_waitcnt vmcnt(2)
	v_mov_b32_e32 v36, 0
	v_mov_b32_e32 v41, 0
	s_and_saveexec_b64 s[58:59], s[10:11]
	s_cbranch_execz .LBB0_851
	ds_read_b32 v40, v105 offset:388
	s_waitcnt lgkmcnt(0)
	v_mul_f32_e32 v41, v141, v40
.LBB0_851:
	s_or_b64 exec, exec, s[58:59]
	s_and_saveexec_b64 s[58:59], s[12:13]
	s_cbranch_execz .LBB0_853
	ds_read_b32 v36, v105 offset:392
	s_waitcnt lgkmcnt(0)
	v_mul_f32_e32 v36, v142, v36
.LBB0_853:
	s_or_b64 exec, exec, s[58:59]
	v_mov_b32_e32 v37, 0
	v_mov_b32_e32 v38, 0
	s_and_saveexec_b64 s[58:59], s[14:15]
	s_cbranch_execz .LBB0_855
	ds_read_b32 v38, v105 offset:396
	s_waitcnt lgkmcnt(0)
	v_mul_f32_e32 v38, v143, v38
.LBB0_855:
	s_or_b64 exec, exec, s[58:59]
	s_and_saveexec_b64 s[58:59], s[16:17]
	s_cbranch_execz .LBB0_857
	ds_read_b32 v37, v105 offset:400
	s_waitcnt lgkmcnt(0)
	v_mul_f32_e32 v37, v136, v37
.LBB0_857:
	s_or_b64 exec, exec, s[58:59]
	v_mov_b32_e32 v32, 0
	v_mov_b32_e32 v39, 0
	s_and_saveexec_b64 s[58:59], s[18:19]
	s_cbranch_execz .LBB0_859
	ds_read_b32 v39, v105 offset:404
	s_waitcnt lgkmcnt(0)
	v_mul_f32_e32 v39, v137, v39
.LBB0_859:
	s_or_b64 exec, exec, s[58:59]
	s_and_saveexec_b64 s[58:59], s[20:21]
	s_cbranch_execz .LBB0_861
	ds_read_b32 v32, v105 offset:408
	s_waitcnt lgkmcnt(0)
	v_mul_f32_e32 v32, v138, v32
.LBB0_861:
	s_or_b64 exec, exec, s[58:59]
	v_mov_b32_e32 v40, 0
	v_mov_b32_e32 v33, 0
	s_and_saveexec_b64 s[58:59], s[22:23]
	s_cbranch_execz .LBB0_863
	ds_read_b32 v33, v105 offset:412
	s_waitcnt lgkmcnt(0)
	v_mul_f32_e32 v33, v139, v33
.LBB0_863:
	s_or_b64 exec, exec, s[58:59]
	v_cvt_pk_bf16_f32 v34, v65, v41
	v_cvt_pk_bf16_f32 v35, v36, v38
	v_cvt_pk_bf16_f32 v36, v37, v39
	v_cvt_pk_bf16_f32 v37, v32, v33
	s_waitcnt vmcnt(1)
	s_nop 0
	v_mfma_f32_32x32x16_bf16 v[16:31], v[144:147], v[34:37], v[16:31]
	s_waitcnt vmcnt(0)
	v_mfma_f32_32x32x16_bf16 v[0:15], v[148:151], v[34:37], v[0:15]
	global_load_dwordx4 v[32:35], v[84:85], off offset:464
	global_load_dwordx4 v[36:39], v[84:85], off offset:448
	s_and_saveexec_b64 s[58:59], s[24:25]
	s_cbranch_execz .LBB0_865
	ds_read_b32 v40, v105 offset:448
	s_waitcnt vmcnt(0) lgkmcnt(0)
	v_mul_f32_e32 v40, v36, v40
